# GEMM mainloops: priority flips inverted (load sections at priority 1, MFMA sections at 0)
# baseline (speedup 1.0000x reference)
.LBB0_288:
	s_add_u32 s30, s28, 0xfffc0080
	s_addc_u32 s31, s29, -1
	s_add_i32 s56, 0, 0x10000
	s_cmp_eq_u32 s55, 12
	s_cselect_b32 s35, s21, s31
	s_cselect_b32 s34, s36, s30
	s_cselect_b32 s31, s19, s39
	s_cselect_b32 s30, s37, s38
	s_add_i32 s58, 0, 0x14000
	v_add_u32_e32 v166, s56, v147
	v_add_u32_e32 v182, s58, v147
	ds_read_b128 v[142:145], v166
	ds_read_b128 v[158:161], v166 offset:1024
	ds_read_b128 v[162:165], v166 offset:2048
	ds_read_b128 v[166:169], v166 offset:3072
	ds_read_b128 v[170:173], v182
	ds_read_b128 v[174:177], v182 offset:1024
	ds_read_b128 v[178:181], v182 offset:2048
	ds_read_b128 v[182:185], v182 offset:3072
	v_lshl_add_u64 v[224:225], s[28:29], 0, v[140:141]
	s_add_i32 m0, s44, 0xc000
	ds_read_b128 v[186:189], v157
	ds_read_b128 v[190:193], v157 offset:1024
	ds_read_b128 v[194:197], v157 offset:2048
	ds_read_b128 v[198:201], v157 offset:3072
	ds_read_b128 v[202:205], v157 offset:4096
	ds_read_b128 v[206:209], v157 offset:5120
	ds_read_b128 v[220:223], v157 offset:6144
	ds_read_b128 v[236:239], v157 offset:7168
	global_load_lds_dwordx4 v[224:225], off
	v_lshl_add_u64 v[224:225], s[28:29], 0, v[138:139]
	s_add_i32 m0, s44, 0xe000
	s_nop 0
	global_load_lds_dwordx4 v[224:225], off
	s_waitcnt vmcnt(8)
	s_waitcnt lgkmcnt(0)
	s_barrier
	s_setprio 0
	s_waitcnt lgkmcnt(0)
	v_mfma_f32_16x16x32_bf16 v[126:129], v[142:145], v[186:189], v[126:129]
	v_mfma_f32_16x16x32_bf16 v[122:125], v[162:165], v[186:189], v[122:125]
	v_mfma_f32_16x16x32_bf16 v[110:113], v[142:145], v[194:197], v[110:113]
	v_mfma_f32_16x16x32_bf16 v[106:109], v[162:165], v[194:197], v[106:109]
	v_mfma_f32_16x16x32_bf16 v[94:97], v[142:145], v[202:205], v[94:97]
	v_mfma_f32_16x16x32_bf16 v[90:93], v[162:165], v[202:205], v[90:93]
	v_mfma_f32_16x16x32_bf16 v[78:81], v[142:145], v[220:223], v[78:81]
	v_mfma_f32_16x16x32_bf16 v[74:77], v[162:165], v[220:223], v[74:77]
	v_mfma_f32_16x16x32_bf16 v[126:129], v[158:161], v[190:193], v[126:129]
	v_mfma_f32_16x16x32_bf16 v[122:125], v[166:169], v[190:193], v[122:125]
	v_mfma_f32_16x16x32_bf16 v[110:113], v[158:161], v[198:201], v[110:113]
	v_mfma_f32_16x16x32_bf16 v[106:109], v[166:169], v[198:201], v[106:109]
	v_mfma_f32_16x16x32_bf16 v[94:97], v[158:161], v[206:209], v[94:97]
	v_mfma_f32_16x16x32_bf16 v[90:93], v[166:169], v[206:209], v[90:93]
	v_mfma_f32_16x16x32_bf16 v[78:81], v[158:161], v[236:239], v[78:81]
	v_mfma_f32_16x16x32_bf16 v[74:77], v[166:169], v[236:239], v[74:77]
	v_mfma_f32_16x16x32_bf16 v[118:121], v[170:173], v[186:189], v[118:121]
	v_mfma_f32_16x16x32_bf16 v[114:117], v[178:181], v[186:189], v[114:117]
	v_mfma_f32_16x16x32_bf16 v[102:105], v[170:173], v[194:197], v[102:105]
	v_mfma_f32_16x16x32_bf16 v[98:101], v[178:181], v[194:197], v[98:101]
	v_mfma_f32_16x16x32_bf16 v[86:89], v[170:173], v[202:205], v[86:89]
	v_mfma_f32_16x16x32_bf16 v[82:85], v[178:181], v[202:205], v[82:85]
	v_mfma_f32_16x16x32_bf16 v[70:73], v[170:173], v[220:223], v[70:73]
	v_mfma_f32_16x16x32_bf16 v[66:69], v[178:181], v[220:223], v[66:69]
	v_mfma_f32_16x16x32_bf16 v[118:121], v[174:177], v[190:193], v[118:121]
	v_mfma_f32_16x16x32_bf16 v[114:117], v[182:185], v[190:193], v[114:117]
	v_mfma_f32_16x16x32_bf16 v[102:105], v[174:177], v[198:201], v[102:105]
	v_mfma_f32_16x16x32_bf16 v[98:101], v[182:185], v[198:201], v[98:101]
	v_mfma_f32_16x16x32_bf16 v[86:89], v[174:177], v[206:209], v[86:89]
	v_mfma_f32_16x16x32_bf16 v[82:85], v[182:185], v[206:209], v[82:85]
	v_mfma_f32_16x16x32_bf16 v[70:73], v[174:177], v[236:239], v[70:73]
	v_mfma_f32_16x16x32_bf16 v[66:69], v[182:185], v[236:239], v[66:69]
	s_setprio 1
	s_barrier
	s_add_i32 s56, s56, s27
	v_lshl_add_u64 v[224:225], s[30:31], 0, v[132:133]
	s_mov_b32 m0, s56
	ds_read_b128 v[186:189], v157 offset:16384
	ds_read_b128 v[190:193], v157 offset:17408
	ds_read_b128 v[194:197], v157 offset:18432
	ds_read_b128 v[198:201], v157 offset:19456
	ds_read_b128 v[202:205], v157 offset:20480
	ds_read_b128 v[206:209], v157 offset:21504
	ds_read_b128 v[220:223], v157 offset:22528
	ds_read_b128 v[236:239], v157 offset:23552
	global_load_lds_dwordx4 v[224:225], off
	s_add_i32 m0, s56, 0x2000
	s_add_u32 s56, s30, 0x40000
	v_lshl_add_u64 v[230:231], s[30:31], 0, v[136:137]
	s_addc_u32 s57, s31, 0
	s_add_i32 s58, s58, s27
	global_load_lds_dwordx4 v[230:231], off
	v_lshl_add_u64 v[240:241], s[56:57], 0, v[132:133]
	s_mov_b32 m0, s58
	v_lshl_add_u64 v[242:243], s[34:35], 0, v[134:135]
	global_load_lds_dwordx4 v[240:241], off
	v_lshl_add_u64 v[240:241], s[56:57], 0, v[136:137]
	s_add_i32 m0, s58, 0x2000
	s_nop 0
	global_load_lds_dwordx4 v[240:241], off
	v_lshl_add_u64 v[240:241], s[34:35], 0, v[130:131]
	s_mov_b32 m0, s44
	s_nop 0
	global_load_lds_dwordx4 v[240:241], off
	s_mov_b32 m0, s45
	s_nop 0
	global_load_lds_dwordx4 v[242:243], off
	s_waitcnt vmcnt(8)
	s_waitcnt lgkmcnt(0)
	s_barrier
	s_setprio 0
	s_waitcnt lgkmcnt(0)
	v_mfma_f32_16x16x32_bf16 v[62:65], v[142:145], v[186:189], v[62:65]
	v_mfma_f32_16x16x32_bf16 v[58:61], v[162:165], v[186:189], v[58:61]
	v_mfma_f32_16x16x32_bf16 v[46:49], v[142:145], v[194:197], v[46:49]
	v_mfma_f32_16x16x32_bf16 v[42:45], v[162:165], v[194:197], v[42:45]
	v_mfma_f32_16x16x32_bf16 v[30:33], v[142:145], v[202:205], v[30:33]
	v_mfma_f32_16x16x32_bf16 v[26:29], v[162:165], v[202:205], v[26:29]
	v_mfma_f32_16x16x32_bf16 v[14:17], v[142:145], v[220:223], v[14:17]
	v_mfma_f32_16x16x32_bf16 v[10:13], v[162:165], v[220:223], v[10:13]
	v_mfma_f32_16x16x32_bf16 v[62:65], v[158:161], v[190:193], v[62:65]
	v_mfma_f32_16x16x32_bf16 v[58:61], v[166:169], v[190:193], v[58:61]
	v_mfma_f32_16x16x32_bf16 v[46:49], v[158:161], v[198:201], v[46:49]
	v_mfma_f32_16x16x32_bf16 v[42:45], v[166:169], v[198:201], v[42:45]
	v_mfma_f32_16x16x32_bf16 v[30:33], v[158:161], v[206:209], v[30:33]
	v_mfma_f32_16x16x32_bf16 v[26:29], v[166:169], v[206:209], v[26:29]
	v_mfma_f32_16x16x32_bf16 v[14:17], v[158:161], v[236:239], v[14:17]
	v_mfma_f32_16x16x32_bf16 v[10:13], v[166:169], v[236:239], v[10:13]
	v_mfma_f32_16x16x32_bf16 v[54:57], v[170:173], v[186:189], v[54:57]
	v_mfma_f32_16x16x32_bf16 v[50:53], v[178:181], v[186:189], v[50:53]
	v_mfma_f32_16x16x32_bf16 v[38:41], v[170:173], v[194:197], v[38:41]
	v_mfma_f32_16x16x32_bf16 v[34:37], v[178:181], v[194:197], v[34:37]
	v_mfma_f32_16x16x32_bf16 v[22:25], v[170:173], v[202:205], v[22:25]
	v_mfma_f32_16x16x32_bf16 v[18:21], v[178:181], v[202:205], v[18:21]
	v_mfma_f32_16x16x32_bf16 v[6:9], v[170:173], v[220:223], v[6:9]
	v_mfma_f32_16x16x32_bf16 v[2:5], v[178:181], v[220:223], v[2:5]
	v_mfma_f32_16x16x32_bf16 v[54:57], v[174:177], v[190:193], v[54:57]
	v_mfma_f32_16x16x32_bf16 v[50:53], v[182:185], v[190:193], v[50:53]
	v_mfma_f32_16x16x32_bf16 v[38:41], v[174:177], v[198:201], v[38:41]
	v_mfma_f32_16x16x32_bf16 v[34:37], v[182:185], v[198:201], v[34:37]
	v_mfma_f32_16x16x32_bf16 v[22:25], v[174:177], v[206:209], v[22:25]
	v_mfma_f32_16x16x32_bf16 v[18:21], v[182:185], v[206:209], v[18:21]
	v_mfma_f32_16x16x32_bf16 v[6:9], v[174:177], v[236:239], v[6:9]
	v_mfma_f32_16x16x32_bf16 v[2:5], v[182:185], v[236:239], v[2:5]
	s_setprio 1
	s_barrier
	s_add_i32 s56, 0, 0x18000
	s_add_i32 s57, 0, 0x1c000
	v_add_u32_e32 v166, s56, v147
	v_add_u32_e32 v182, s57, v147
	ds_read_b128 v[142:145], v166
	ds_read_b128 v[158:161], v166 offset:1024
	ds_read_b128 v[162:165], v166 offset:2048
	ds_read_b128 v[166:169], v166 offset:3072
	ds_read_b128 v[170:173], v182
	ds_read_b128 v[174:177], v182 offset:1024
	ds_read_b128 v[178:181], v182 offset:2048
	ds_read_b128 v[182:185], v182 offset:3072
	s_add_u32 s34, s34, 0x40000
	s_addc_u32 s35, s35, 0
	s_mov_b32 m0, s43
	v_lshl_add_u64 v[244:245], s[34:35], 0, v[130:131]
	ds_read_b128 v[186:189], v157 offset:32768
	ds_read_b128 v[190:193], v157 offset:33792
	ds_read_b128 v[194:197], v157 offset:34816
	ds_read_b128 v[198:201], v157 offset:35840
	ds_read_b128 v[202:205], v157 offset:36864
	ds_read_b128 v[206:209], v157 offset:37888
	ds_read_b128 v[220:223], v157 offset:38912
	ds_read_b128 v[236:239], v157 offset:39936
	global_load_lds_dwordx4 v[244:245], off
	v_lshl_add_u64 v[244:245], s[34:35], 0, v[134:135]
	s_mov_b32 m0, s46
	s_nop 0
	global_load_lds_dwordx4 v[244:245], off
	s_waitcnt vmcnt(8)
	s_waitcnt lgkmcnt(0)
	s_barrier
	s_setprio 0
	s_waitcnt lgkmcnt(0)
	v_mfma_f32_16x16x32_bf16 v[126:129], v[142:145], v[186:189], v[126:129]
	v_mfma_f32_16x16x32_bf16 v[122:125], v[162:165], v[186:189], v[122:125]
	v_mfma_f32_16x16x32_bf16 v[110:113], v[142:145], v[194:197], v[110:113]
	v_mfma_f32_16x16x32_bf16 v[106:109], v[162:165], v[194:197], v[106:109]
	v_mfma_f32_16x16x32_bf16 v[94:97], v[142:145], v[202:205], v[94:97]
	v_mfma_f32_16x16x32_bf16 v[90:93], v[162:165], v[202:205], v[90:93]
	v_mfma_f32_16x16x32_bf16 v[78:81], v[142:145], v[220:223], v[78:81]
	v_mfma_f32_16x16x32_bf16 v[74:77], v[162:165], v[220:223], v[74:77]
	v_mfma_f32_16x16x32_bf16 v[126:129], v[158:161], v[190:193], v[126:129]
	v_mfma_f32_16x16x32_bf16 v[122:125], v[166:169], v[190:193], v[122:125]
	v_mfma_f32_16x16x32_bf16 v[110:113], v[158:161], v[198:201], v[110:113]
	v_mfma_f32_16x16x32_bf16 v[106:109], v[166:169], v[198:201], v[106:109]
	v_mfma_f32_16x16x32_bf16 v[94:97], v[158:161], v[206:209], v[94:97]
	v_mfma_f32_16x16x32_bf16 v[90:93], v[166:169], v[206:209], v[90:93]
	v_mfma_f32_16x16x32_bf16 v[78:81], v[158:161], v[236:239], v[78:81]
	v_mfma_f32_16x16x32_bf16 v[74:77], v[166:169], v[236:239], v[74:77]
	v_mfma_f32_16x16x32_bf16 v[118:121], v[170:173], v[186:189], v[118:121]
	v_mfma_f32_16x16x32_bf16 v[114:117], v[178:181], v[186:189], v[114:117]
	v_mfma_f32_16x16x32_bf16 v[102:105], v[170:173], v[194:197], v[102:105]
	v_mfma_f32_16x16x32_bf16 v[98:101], v[178:181], v[194:197], v[98:101]
	v_mfma_f32_16x16x32_bf16 v[86:89], v[170:173], v[202:205], v[86:89]
	v_mfma_f32_16x16x32_bf16 v[82:85], v[178:181], v[202:205], v[82:85]
	v_mfma_f32_16x16x32_bf16 v[70:73], v[170:173], v[220:223], v[70:73]
	v_mfma_f32_16x16x32_bf16 v[66:69], v[178:181], v[220:223], v[66:69]
	v_mfma_f32_16x16x32_bf16 v[118:121], v[174:177], v[190:193], v[118:121]
	v_mfma_f32_16x16x32_bf16 v[114:117], v[182:185], v[190:193], v[114:117]
	v_mfma_f32_16x16x32_bf16 v[102:105], v[174:177], v[198:201], v[102:105]
	v_mfma_f32_16x16x32_bf16 v[98:101], v[182:185], v[198:201], v[98:101]
	v_mfma_f32_16x16x32_bf16 v[86:89], v[174:177], v[206:209], v[86:89]
	v_mfma_f32_16x16x32_bf16 v[82:85], v[182:185], v[206:209], v[82:85]
	v_mfma_f32_16x16x32_bf16 v[70:73], v[174:177], v[236:239], v[70:73]
	v_mfma_f32_16x16x32_bf16 v[66:69], v[182:185], v[236:239], v[66:69]
	s_setprio 1
	s_barrier
	s_add_i32 s34, s56, s27
	v_lshl_add_u64 v[224:225], v[224:225], 0, s[96:97]
	s_mov_b32 m0, s34
	ds_read_b128 v[186:189], v157 offset:49152
	ds_read_b128 v[190:193], v157 offset:50176
	ds_read_b128 v[194:197], v157 offset:51200
	ds_read_b128 v[198:201], v157 offset:52224
	ds_read_b128 v[202:205], v157 offset:53248
	ds_read_b128 v[206:209], v157 offset:54272
	ds_read_b128 v[220:223], v157 offset:55296
	ds_read_b128 v[236:239], v157 offset:56320
	global_load_lds_dwordx4 v[224:225], off
	s_add_i32 m0, s34, 0x2000
	s_add_u32 s30, s30, 0x40080
	v_lshl_add_u64 v[224:225], v[230:231], 0, s[96:97]
	s_addc_u32 s31, s31, 0
	s_add_i32 s34, s57, s27
	global_load_lds_dwordx4 v[224:225], off
	v_lshl_add_u64 v[224:225], s[30:31], 0, v[132:133]
	s_mov_b32 m0, s34
	s_nop 0
	global_load_lds_dwordx4 v[224:225], off
	v_lshl_add_u64 v[224:225], s[30:31], 0, v[136:137]
	s_add_i32 m0, s34, 0x2000
	s_nop 0
	global_load_lds_dwordx4 v[224:225], off
	v_lshl_add_u64 v[224:225], v[240:241], 0, s[96:97]
	s_mov_b32 m0, s47
	s_nop 0
	global_load_lds_dwordx4 v[224:225], off
	v_lshl_add_u64 v[224:225], v[242:243], 0, s[96:97]
	s_mov_b32 m0, s48
	s_nop 0
	global_load_lds_dwordx4 v[224:225], off
	s_waitcnt vmcnt(8)
	s_waitcnt lgkmcnt(0)
	s_barrier
	s_setprio 0
	s_waitcnt lgkmcnt(0)
	v_mfma_f32_16x16x32_bf16 v[62:65], v[142:145], v[186:189], v[62:65]
	v_mfma_f32_16x16x32_bf16 v[58:61], v[162:165], v[186:189], v[58:61]
	v_mfma_f32_16x16x32_bf16 v[46:49], v[142:145], v[194:197], v[46:49]
	v_mfma_f32_16x16x32_bf16 v[42:45], v[162:165], v[194:197], v[42:45]
	v_mfma_f32_16x16x32_bf16 v[30:33], v[142:145], v[202:205], v[30:33]
	v_mfma_f32_16x16x32_bf16 v[26:29], v[162:165], v[202:205], v[26:29]
	v_mfma_f32_16x16x32_bf16 v[14:17], v[142:145], v[220:223], v[14:17]
	v_mfma_f32_16x16x32_bf16 v[10:13], v[162:165], v[220:223], v[10:13]
	v_mfma_f32_16x16x32_bf16 v[62:65], v[158:161], v[190:193], v[62:65]
	v_mfma_f32_16x16x32_bf16 v[58:61], v[166:169], v[190:193], v[58:61]
	v_mfma_f32_16x16x32_bf16 v[46:49], v[158:161], v[198:201], v[46:49]
	v_mfma_f32_16x16x32_bf16 v[42:45], v[166:169], v[198:201], v[42:45]
	v_mfma_f32_16x16x32_bf16 v[30:33], v[158:161], v[206:209], v[30:33]
	v_mfma_f32_16x16x32_bf16 v[26:29], v[166:169], v[206:209], v[26:29]
	v_mfma_f32_16x16x32_bf16 v[14:17], v[158:161], v[236:239], v[14:17]
	v_mfma_f32_16x16x32_bf16 v[10:13], v[166:169], v[236:239], v[10:13]
	v_mfma_f32_16x16x32_bf16 v[54:57], v[170:173], v[186:189], v[54:57]
	v_mfma_f32_16x16x32_bf16 v[50:53], v[178:181], v[186:189], v[50:53]
	v_mfma_f32_16x16x32_bf16 v[38:41], v[170:173], v[194:197], v[38:41]
	v_mfma_f32_16x16x32_bf16 v[34:37], v[178:181], v[194:197], v[34:37]
	v_mfma_f32_16x16x32_bf16 v[22:25], v[170:173], v[202:205], v[22:25]
	v_mfma_f32_16x16x32_bf16 v[18:21], v[178:181], v[202:205], v[18:21]
	v_mfma_f32_16x16x32_bf16 v[6:9], v[170:173], v[220:223], v[6:9]
	v_mfma_f32_16x16x32_bf16 v[2:5], v[178:181], v[220:223], v[2:5]
	v_mfma_f32_16x16x32_bf16 v[54:57], v[174:177], v[190:193], v[54:57]
	v_mfma_f32_16x16x32_bf16 v[50:53], v[182:185], v[190:193], v[50:53]
	v_mfma_f32_16x16x32_bf16 v[38:41], v[174:177], v[198:201], v[38:41]
	v_mfma_f32_16x16x32_bf16 v[34:37], v[182:185], v[198:201], v[34:37]
	v_mfma_f32_16x16x32_bf16 v[22:25], v[174:177], v[206:209], v[22:25]
	v_mfma_f32_16x16x32_bf16 v[18:21], v[182:185], v[206:209], v[18:21]
	v_mfma_f32_16x16x32_bf16 v[6:9], v[174:177], v[236:239], v[6:9]
	v_mfma_f32_16x16x32_bf16 v[2:5], v[182:185], v[236:239], v[2:5]
	s_setprio 1
	s_barrier
	s_add_i32 s55, s55, 2
	s_add_u32 s38, s38, 0x100
	s_addc_u32 s39, s39, 0
	s_add_u32 s28, s28, 0x100
	s_addc_u32 s29, s29, 0
	s_cmp_gt_u32 s55, 13
	s_cbranch_scc0 .LBB0_288
	s_and_b64 vcc, exec, s[12:13]
	s_cbranch_vccz .LBB0_291
	s_barrier

.LBB0_363:
	s_add_u32 s34, s30, 0xfffc0080
	s_addc_u32 s35, s31, -1
	s_add_i32 s57, 0, 0x10000
	s_cmp_eq_u32 s56, 12
	s_cselect_b32 s37, s23, s35
	s_cselect_b32 s36, s39, s34
	v_add_u32_e32 v146, s57, v155
	s_cselect_b32 s35, s21, s43
	s_cselect_b32 s34, s40, s41
	s_add_i32 s60, 0, 0x14000
	ds_read_b128 v[142:145], v146
	ds_read_b128 v[168:171], v146 offset:1024
	ds_read_b128 v[172:175], v146 offset:2048
	ds_read_b128 v[176:179], v146 offset:3072
	v_add_u32_e32 v146, s60, v155
	ds_read_b128 v[180:183], v146
	ds_read_b128 v[184:187], v146 offset:1024
	ds_read_b128 v[188:191], v146 offset:2048
	ds_read_b128 v[192:195], v146 offset:3072
	v_lshl_add_u64 v[146:147], s[30:31], 0, v[140:141]
	s_add_i32 m0, s48, 0xc000
	ds_read_b128 v[196:199], v157
	ds_read_b128 v[200:203], v157 offset:1024
	ds_read_b128 v[204:207], v157 offset:2048
	ds_read_b128 v[220:223], v157 offset:3072
	ds_read_b128 v[236:239], v157 offset:4096
	ds_read_b128 v[240:243], v157 offset:5120
	ds_read_b128 v[244:247], v157 offset:6144
	ds_read_b128 v[248:251], v157 offset:7168
	global_load_lds_dwordx4 v[146:147], off
	v_lshl_add_u64 v[146:147], s[30:31], 0, v[138:139]
	s_add_i32 m0, s48, 0xe000
	s_nop 0
	global_load_lds_dwordx4 v[146:147], off
	s_waitcnt vmcnt(8)
	s_waitcnt lgkmcnt(0)
	s_barrier
	s_setprio 0
	s_waitcnt lgkmcnt(0)
	v_mfma_f32_16x16x32_bf16 v[126:129], v[142:145], v[196:199], v[126:129]
	v_mfma_f32_16x16x32_bf16 v[118:121], v[172:175], v[196:199], v[118:121]
	v_mfma_f32_16x16x32_bf16 v[110:113], v[142:145], v[204:207], v[110:113]
	v_mfma_f32_16x16x32_bf16 v[102:105], v[172:175], v[204:207], v[102:105]
	v_mfma_f32_16x16x32_bf16 v[94:97], v[142:145], v[236:239], v[94:97]
	v_mfma_f32_16x16x32_bf16 v[86:89], v[172:175], v[236:239], v[86:89]
	v_mfma_f32_16x16x32_bf16 v[78:81], v[142:145], v[244:247], v[78:81]
	v_mfma_f32_16x16x32_bf16 v[70:73], v[172:175], v[244:247], v[70:73]
	v_mfma_f32_16x16x32_bf16 v[126:129], v[168:171], v[200:203], v[126:129]
	v_mfma_f32_16x16x32_bf16 v[118:121], v[176:179], v[200:203], v[118:121]
	v_mfma_f32_16x16x32_bf16 v[110:113], v[168:171], v[220:223], v[110:113]
	v_mfma_f32_16x16x32_bf16 v[102:105], v[176:179], v[220:223], v[102:105]
	v_mfma_f32_16x16x32_bf16 v[94:97], v[168:171], v[240:243], v[94:97]
	v_mfma_f32_16x16x32_bf16 v[86:89], v[176:179], v[240:243], v[86:89]
	v_mfma_f32_16x16x32_bf16 v[78:81], v[168:171], v[248:251], v[78:81]
	v_mfma_f32_16x16x32_bf16 v[70:73], v[176:179], v[248:251], v[70:73]
	v_mfma_f32_16x16x32_bf16 v[122:125], v[180:183], v[196:199], v[122:125]
	v_mfma_f32_16x16x32_bf16 v[114:117], v[188:191], v[196:199], v[114:117]
	v_mfma_f32_16x16x32_bf16 v[106:109], v[180:183], v[204:207], v[106:109]
	v_mfma_f32_16x16x32_bf16 v[98:101], v[188:191], v[204:207], v[98:101]
	v_mfma_f32_16x16x32_bf16 v[90:93], v[180:183], v[236:239], v[90:93]
	v_mfma_f32_16x16x32_bf16 v[82:85], v[188:191], v[236:239], v[82:85]
	v_mfma_f32_16x16x32_bf16 v[74:77], v[180:183], v[244:247], v[74:77]
	v_mfma_f32_16x16x32_bf16 v[66:69], v[188:191], v[244:247], v[66:69]
	v_mfma_f32_16x16x32_bf16 v[122:125], v[184:187], v[200:203], v[122:125]
	v_mfma_f32_16x16x32_bf16 v[114:117], v[192:195], v[200:203], v[114:117]
	v_mfma_f32_16x16x32_bf16 v[106:109], v[184:187], v[220:223], v[106:109]
	v_mfma_f32_16x16x32_bf16 v[98:101], v[192:195], v[220:223], v[98:101]
	v_mfma_f32_16x16x32_bf16 v[90:93], v[184:187], v[240:243], v[90:93]
	v_mfma_f32_16x16x32_bf16 v[82:85], v[192:195], v[240:243], v[82:85]
	v_mfma_f32_16x16x32_bf16 v[74:77], v[184:187], v[248:251], v[74:77]
	v_mfma_f32_16x16x32_bf16 v[66:69], v[192:195], v[248:251], v[66:69]
	s_setprio 1
	s_barrier
	s_add_i32 s57, s57, s44
	v_lshl_add_u64 v[146:147], s[34:35], 0, v[134:135]
	s_mov_b32 m0, s57
	ds_read_b128 v[196:199], v157 offset:16384
	ds_read_b128 v[200:203], v157 offset:17408
	ds_read_b128 v[204:207], v157 offset:18432
	ds_read_b128 v[220:223], v157 offset:19456
	ds_read_b128 v[236:239], v157 offset:20480
	ds_read_b128 v[240:243], v157 offset:21504
	ds_read_b128 v[244:247], v157 offset:22528
	ds_read_b128 v[248:251], v157 offset:23552
	global_load_lds_dwordx4 v[146:147], off
	s_add_i32 m0, s57, 0x2000
	s_add_u32 s58, s34, 0x40000
	v_lshl_add_u64 v[208:209], s[34:35], 0, v[130:131]
	s_addc_u32 s59, s35, 0
	s_add_i32 s57, s60, s44
	global_load_lds_dwordx4 v[208:209], off
	v_lshl_add_u64 v[224:225], s[58:59], 0, v[134:135]
	s_mov_b32 m0, s57
	v_lshl_add_u64 v[230:231], s[36:37], 0, v[132:133]
	global_load_lds_dwordx4 v[224:225], off
	v_lshl_add_u64 v[224:225], s[58:59], 0, v[130:131]
	s_add_i32 m0, s57, 0x2000
	s_nop 0
	global_load_lds_dwordx4 v[224:225], off
	v_lshl_add_u64 v[224:225], s[36:37], 0, v[136:137]
	s_mov_b32 m0, s48
	s_nop 0
	global_load_lds_dwordx4 v[224:225], off
	s_mov_b32 m0, s49
	s_nop 0
	global_load_lds_dwordx4 v[230:231], off
	s_waitcnt vmcnt(8)
	s_waitcnt lgkmcnt(0)
	s_barrier
	s_setprio 0
	s_waitcnt lgkmcnt(0)
	v_mfma_f32_16x16x32_bf16 v[62:65], v[142:145], v[196:199], v[62:65]
	v_mfma_f32_16x16x32_bf16 v[54:57], v[172:175], v[196:199], v[54:57]
	v_mfma_f32_16x16x32_bf16 v[46:49], v[142:145], v[204:207], v[46:49]
	v_mfma_f32_16x16x32_bf16 v[38:41], v[172:175], v[204:207], v[38:41]
	v_mfma_f32_16x16x32_bf16 v[30:33], v[142:145], v[236:239], v[30:33]
	v_mfma_f32_16x16x32_bf16 v[22:25], v[172:175], v[236:239], v[22:25]
	v_mfma_f32_16x16x32_bf16 v[14:17], v[142:145], v[244:247], v[14:17]
	v_mfma_f32_16x16x32_bf16 v[6:9], v[172:175], v[244:247], v[6:9]
	v_mfma_f32_16x16x32_bf16 v[62:65], v[168:171], v[200:203], v[62:65]
	v_mfma_f32_16x16x32_bf16 v[54:57], v[176:179], v[200:203], v[54:57]
	v_mfma_f32_16x16x32_bf16 v[46:49], v[168:171], v[220:223], v[46:49]
	v_mfma_f32_16x16x32_bf16 v[38:41], v[176:179], v[220:223], v[38:41]
	v_mfma_f32_16x16x32_bf16 v[30:33], v[168:171], v[240:243], v[30:33]
	v_mfma_f32_16x16x32_bf16 v[22:25], v[176:179], v[240:243], v[22:25]
	v_mfma_f32_16x16x32_bf16 v[14:17], v[168:171], v[248:251], v[14:17]
	v_mfma_f32_16x16x32_bf16 v[6:9], v[176:179], v[248:251], v[6:9]
	v_mfma_f32_16x16x32_bf16 v[58:61], v[180:183], v[196:199], v[58:61]
	v_mfma_f32_16x16x32_bf16 v[50:53], v[188:191], v[196:199], v[50:53]
	v_mfma_f32_16x16x32_bf16 v[42:45], v[180:183], v[204:207], v[42:45]
	v_mfma_f32_16x16x32_bf16 v[34:37], v[188:191], v[204:207], v[34:37]
	v_mfma_f32_16x16x32_bf16 v[26:29], v[180:183], v[236:239], v[26:29]
	v_mfma_f32_16x16x32_bf16 v[18:21], v[188:191], v[236:239], v[18:21]
	v_mfma_f32_16x16x32_bf16 v[10:13], v[180:183], v[244:247], v[10:13]
	v_mfma_f32_16x16x32_bf16 v[2:5], v[188:191], v[244:247], v[2:5]
	v_mfma_f32_16x16x32_bf16 v[58:61], v[184:187], v[200:203], v[58:61]
	v_mfma_f32_16x16x32_bf16 v[50:53], v[192:195], v[200:203], v[50:53]
	v_mfma_f32_16x16x32_bf16 v[42:45], v[184:187], v[220:223], v[42:45]
	v_mfma_f32_16x16x32_bf16 v[34:37], v[192:195], v[220:223], v[34:37]
	v_mfma_f32_16x16x32_bf16 v[26:29], v[184:187], v[240:243], v[26:29]
	v_mfma_f32_16x16x32_bf16 v[18:21], v[192:195], v[240:243], v[18:21]
	v_mfma_f32_16x16x32_bf16 v[10:13], v[184:187], v[248:251], v[10:13]
	v_mfma_f32_16x16x32_bf16 v[2:5], v[192:195], v[248:251], v[2:5]
	s_setprio 1
	s_barrier
	s_add_i32 s57, 0, 0x18000
	v_add_u32_e32 v164, s57, v155
	s_add_i32 s58, 0, 0x1c000
	ds_read_b128 v[142:145], v164
	ds_read_b128 v[168:171], v164 offset:1024
	ds_read_b128 v[172:175], v164 offset:2048
	ds_read_b128 v[176:179], v164 offset:3072
	v_add_u32_e32 v164, s58, v155
	ds_read_b128 v[180:183], v164
	ds_read_b128 v[184:187], v164 offset:1024
	ds_read_b128 v[188:191], v164 offset:2048
	ds_read_b128 v[192:195], v164 offset:3072
	s_add_u32 s36, s36, 0x40000
	s_addc_u32 s37, s37, 0
	s_mov_b32 m0, s50
	v_lshl_add_u64 v[252:253], s[36:37], 0, v[136:137]
	ds_read_b128 v[196:199], v157 offset:32768
	ds_read_b128 v[200:203], v157 offset:33792
	ds_read_b128 v[204:207], v157 offset:34816
	ds_read_b128 v[220:223], v157 offset:35840
	ds_read_b128 v[236:239], v157 offset:36864
	ds_read_b128 v[240:243], v157 offset:37888
	ds_read_b128 v[244:247], v157 offset:38912
	ds_read_b128 v[248:251], v157 offset:39936
	global_load_lds_dwordx4 v[252:253], off
	v_lshl_add_u64 v[252:253], s[36:37], 0, v[132:133]
	s_mov_b32 m0, s51
	s_nop 0
	global_load_lds_dwordx4 v[252:253], off
	s_waitcnt vmcnt(8)
	s_waitcnt lgkmcnt(0)
	s_barrier
	s_setprio 0
	s_waitcnt lgkmcnt(0)
	v_mfma_f32_16x16x32_bf16 v[126:129], v[142:145], v[196:199], v[126:129]
	v_mfma_f32_16x16x32_bf16 v[118:121], v[172:175], v[196:199], v[118:121]
	v_mfma_f32_16x16x32_bf16 v[110:113], v[142:145], v[204:207], v[110:113]
	v_mfma_f32_16x16x32_bf16 v[102:105], v[172:175], v[204:207], v[102:105]
	v_mfma_f32_16x16x32_bf16 v[94:97], v[142:145], v[236:239], v[94:97]
	v_mfma_f32_16x16x32_bf16 v[86:89], v[172:175], v[236:239], v[86:89]
	v_mfma_f32_16x16x32_bf16 v[78:81], v[142:145], v[244:247], v[78:81]
	v_mfma_f32_16x16x32_bf16 v[70:73], v[172:175], v[244:247], v[70:73]
	v_mfma_f32_16x16x32_bf16 v[126:129], v[168:171], v[200:203], v[126:129]
	v_mfma_f32_16x16x32_bf16 v[118:121], v[176:179], v[200:203], v[118:121]
	v_mfma_f32_16x16x32_bf16 v[110:113], v[168:171], v[220:223], v[110:113]
	v_mfma_f32_16x16x32_bf16 v[102:105], v[176:179], v[220:223], v[102:105]
	v_mfma_f32_16x16x32_bf16 v[94:97], v[168:171], v[240:243], v[94:97]
	v_mfma_f32_16x16x32_bf16 v[86:89], v[176:179], v[240:243], v[86:89]
	v_mfma_f32_16x16x32_bf16 v[78:81], v[168:171], v[248:251], v[78:81]
	v_mfma_f32_16x16x32_bf16 v[70:73], v[176:179], v[248:251], v[70:73]
	v_mfma_f32_16x16x32_bf16 v[122:125], v[180:183], v[196:199], v[122:125]
	v_mfma_f32_16x16x32_bf16 v[114:117], v[188:191], v[196:199], v[114:117]
	v_mfma_f32_16x16x32_bf16 v[106:109], v[180:183], v[204:207], v[106:109]
	v_mfma_f32_16x16x32_bf16 v[98:101], v[188:191], v[204:207], v[98:101]
	v_mfma_f32_16x16x32_bf16 v[90:93], v[180:183], v[236:239], v[90:93]
	v_mfma_f32_16x16x32_bf16 v[82:85], v[188:191], v[236:239], v[82:85]
	v_mfma_f32_16x16x32_bf16 v[74:77], v[180:183], v[244:247], v[74:77]
	v_mfma_f32_16x16x32_bf16 v[66:69], v[188:191], v[244:247], v[66:69]
	v_mfma_f32_16x16x32_bf16 v[122:125], v[184:187], v[200:203], v[122:125]
	v_mfma_f32_16x16x32_bf16 v[114:117], v[192:195], v[200:203], v[114:117]
	v_mfma_f32_16x16x32_bf16 v[106:109], v[184:187], v[220:223], v[106:109]
	v_mfma_f32_16x16x32_bf16 v[98:101], v[192:195], v[220:223], v[98:101]
	v_mfma_f32_16x16x32_bf16 v[90:93], v[184:187], v[240:243], v[90:93]
	v_mfma_f32_16x16x32_bf16 v[82:85], v[192:195], v[240:243], v[82:85]
	v_mfma_f32_16x16x32_bf16 v[74:77], v[184:187], v[248:251], v[74:77]
	v_mfma_f32_16x16x32_bf16 v[66:69], v[192:195], v[248:251], v[66:69]
	s_setprio 1
	s_barrier
	s_add_i32 s36, s57, s44
	v_lshl_add_u64 v[146:147], v[146:147], 0, s[96:97]
	s_mov_b32 m0, s36
	ds_read_b128 v[196:199], v157 offset:49152
	ds_read_b128 v[200:203], v157 offset:50176
	ds_read_b128 v[204:207], v157 offset:51200
	ds_read_b128 v[220:223], v157 offset:52224
	ds_read_b128 v[236:239], v157 offset:53248
	ds_read_b128 v[240:243], v157 offset:54272
	ds_read_b128 v[244:247], v157 offset:55296
	ds_read_b128 v[248:251], v157 offset:56320
	global_load_lds_dwordx4 v[146:147], off
	s_add_i32 m0, s36, 0x2000
	s_add_u32 s34, s34, 0x40080
	v_lshl_add_u64 v[146:147], v[208:209], 0, s[96:97]
	s_addc_u32 s35, s35, 0
	s_add_i32 s36, s58, s44
	global_load_lds_dwordx4 v[146:147], off
	v_lshl_add_u64 v[146:147], s[34:35], 0, v[134:135]
	s_mov_b32 m0, s36
	s_nop 0
	global_load_lds_dwordx4 v[146:147], off
	v_lshl_add_u64 v[146:147], s[34:35], 0, v[130:131]
	s_add_i32 m0, s36, 0x2000
	s_nop 0
	global_load_lds_dwordx4 v[146:147], off
	v_lshl_add_u64 v[146:147], v[224:225], 0, s[96:97]
	s_mov_b32 m0, s52
	s_nop 0
	global_load_lds_dwordx4 v[146:147], off
	v_lshl_add_u64 v[146:147], v[230:231], 0, s[96:97]
	s_mov_b32 m0, s53
	s_nop 0
	global_load_lds_dwordx4 v[146:147], off
	s_waitcnt vmcnt(8)
	s_waitcnt lgkmcnt(0)
	s_barrier
	s_setprio 0
	s_waitcnt lgkmcnt(0)
	v_mfma_f32_16x16x32_bf16 v[62:65], v[142:145], v[196:199], v[62:65]
	v_mfma_f32_16x16x32_bf16 v[54:57], v[172:175], v[196:199], v[54:57]
	v_mfma_f32_16x16x32_bf16 v[46:49], v[142:145], v[204:207], v[46:49]
	v_mfma_f32_16x16x32_bf16 v[38:41], v[172:175], v[204:207], v[38:41]
	v_mfma_f32_16x16x32_bf16 v[30:33], v[142:145], v[236:239], v[30:33]
	v_mfma_f32_16x16x32_bf16 v[22:25], v[172:175], v[236:239], v[22:25]
	v_mfma_f32_16x16x32_bf16 v[14:17], v[142:145], v[244:247], v[14:17]
	v_mfma_f32_16x16x32_bf16 v[6:9], v[172:175], v[244:247], v[6:9]
	v_mfma_f32_16x16x32_bf16 v[62:65], v[168:171], v[200:203], v[62:65]
	v_mfma_f32_16x16x32_bf16 v[54:57], v[176:179], v[200:203], v[54:57]
	v_mfma_f32_16x16x32_bf16 v[46:49], v[168:171], v[220:223], v[46:49]
	v_mfma_f32_16x16x32_bf16 v[38:41], v[176:179], v[220:223], v[38:41]
	v_mfma_f32_16x16x32_bf16 v[30:33], v[168:171], v[240:243], v[30:33]
	v_mfma_f32_16x16x32_bf16 v[22:25], v[176:179], v[240:243], v[22:25]
	v_mfma_f32_16x16x32_bf16 v[14:17], v[168:171], v[248:251], v[14:17]
	v_mfma_f32_16x16x32_bf16 v[6:9], v[176:179], v[248:251], v[6:9]
	v_mfma_f32_16x16x32_bf16 v[58:61], v[180:183], v[196:199], v[58:61]
	v_mfma_f32_16x16x32_bf16 v[50:53], v[188:191], v[196:199], v[50:53]
	v_mfma_f32_16x16x32_bf16 v[42:45], v[180:183], v[204:207], v[42:45]
	v_mfma_f32_16x16x32_bf16 v[34:37], v[188:191], v[204:207], v[34:37]
	v_mfma_f32_16x16x32_bf16 v[26:29], v[180:183], v[236:239], v[26:29]
	v_mfma_f32_16x16x32_bf16 v[18:21], v[188:191], v[236:239], v[18:21]
	v_mfma_f32_16x16x32_bf16 v[10:13], v[180:183], v[244:247], v[10:13]
	v_mfma_f32_16x16x32_bf16 v[2:5], v[188:191], v[244:247], v[2:5]
	v_mfma_f32_16x16x32_bf16 v[58:61], v[184:187], v[200:203], v[58:61]
	v_mfma_f32_16x16x32_bf16 v[50:53], v[192:195], v[200:203], v[50:53]
	v_mfma_f32_16x16x32_bf16 v[42:45], v[184:187], v[220:223], v[42:45]
	v_mfma_f32_16x16x32_bf16 v[34:37], v[192:195], v[220:223], v[34:37]
	v_mfma_f32_16x16x32_bf16 v[26:29], v[184:187], v[240:243], v[26:29]
	v_mfma_f32_16x16x32_bf16 v[18:21], v[192:195], v[240:243], v[18:21]
	v_mfma_f32_16x16x32_bf16 v[10:13], v[184:187], v[248:251], v[10:13]
	v_mfma_f32_16x16x32_bf16 v[2:5], v[192:195], v[248:251], v[2:5]
	s_setprio 1
	s_barrier
	s_add_i32 s56, s56, 2
	s_add_u32 s41, s41, 0x100
	s_addc_u32 s43, s43, 0
	s_add_u32 s30, s30, 0x100
	s_addc_u32 s31, s31, 0
	s_cmp_gt_u32 s56, 13
	s_cbranch_scc0 .LBB0_363
	s_and_b64 vcc, exec, s[16:17]
	s_cbranch_vccz .LBB0_366
	s_barrier

.LBB0_476:
	s_add_i32 s63, s31, 2
	s_add_u32 s38, s28, s36
	s_addc_u32 s39, s29, s37
	s_add_u32 s64, s26, s36
	s_addc_u32 s65, s27, s37
	s_add_i32 s66, 0, 0x10000
	s_cmp_eq_u32 s59, s31
	s_cselect_b32 s39, s9, s39
	s_cselect_b32 s38, s8, s38
	s_cselect_b32 s65, s35, s65
	s_cselect_b32 s64, s34, s64
	s_add_i32 s31, 0, 0x14000
	v_add_u32_e32 v160, s66, v146
	v_add_u32_e32 v176, s31, v146
	ds_read_b128 v[148:151], v160
	ds_read_b128 v[152:155], v160 offset:1024
	ds_read_b128 v[156:159], v160 offset:2048
	ds_read_b128 v[160:163], v160 offset:3072
	ds_read_b128 v[164:167], v176
	ds_read_b128 v[168:171], v176 offset:1024
	ds_read_b128 v[172:175], v176 offset:2048
	ds_read_b128 v[176:179], v176 offset:3072
	v_lshl_add_u64 v[208:209], s[28:29], 0, v[142:143]
	s_add_i32 m0, s51, 0xc000
	ds_read_b128 v[180:183], v147
	ds_read_b128 v[184:187], v147 offset:1024
	ds_read_b128 v[188:191], v147 offset:2048
	ds_read_b128 v[192:195], v147 offset:3072
	ds_read_b128 v[196:199], v147 offset:4096
	ds_read_b128 v[200:203], v147 offset:5120
	ds_read_b128 v[204:207], v147 offset:6144
	ds_read_b128 v[220:223], v147 offset:7168
	global_load_lds_dwordx4 v[208:209], off
	v_lshl_add_u64 v[208:209], s[28:29], 0, v[144:145]
	s_add_i32 m0, s51, 0xe000
	s_nop 0
	global_load_lds_dwordx4 v[208:209], off
	s_waitcnt vmcnt(8)
	s_waitcnt lgkmcnt(0)
	s_barrier
	s_setprio 0
	s_waitcnt lgkmcnt(0)
	v_mfma_f32_16x16x32_bf16 v[126:129], v[148:151], v[180:183], v[126:129]
	v_mfma_f32_16x16x32_bf16 v[122:125], v[156:159], v[180:183], v[122:125]
	v_mfma_f32_16x16x32_bf16 v[110:113], v[148:151], v[188:191], v[110:113]
	v_mfma_f32_16x16x32_bf16 v[106:109], v[156:159], v[188:191], v[106:109]
	v_mfma_f32_16x16x32_bf16 v[94:97], v[148:151], v[196:199], v[94:97]
	v_mfma_f32_16x16x32_bf16 v[90:93], v[156:159], v[196:199], v[90:93]
	v_mfma_f32_16x16x32_bf16 v[78:81], v[148:151], v[204:207], v[78:81]
	v_mfma_f32_16x16x32_bf16 v[74:77], v[156:159], v[204:207], v[74:77]
	v_mfma_f32_16x16x32_bf16 v[126:129], v[152:155], v[184:187], v[126:129]
	v_mfma_f32_16x16x32_bf16 v[122:125], v[160:163], v[184:187], v[122:125]
	v_mfma_f32_16x16x32_bf16 v[110:113], v[152:155], v[192:195], v[110:113]
	v_mfma_f32_16x16x32_bf16 v[106:109], v[160:163], v[192:195], v[106:109]
	v_mfma_f32_16x16x32_bf16 v[94:97], v[152:155], v[200:203], v[94:97]
	v_mfma_f32_16x16x32_bf16 v[90:93], v[160:163], v[200:203], v[90:93]
	v_mfma_f32_16x16x32_bf16 v[78:81], v[152:155], v[220:223], v[78:81]
	v_mfma_f32_16x16x32_bf16 v[74:77], v[160:163], v[220:223], v[74:77]
	v_mfma_f32_16x16x32_bf16 v[118:121], v[164:167], v[180:183], v[118:121]
	v_mfma_f32_16x16x32_bf16 v[114:117], v[172:175], v[180:183], v[114:117]
	v_mfma_f32_16x16x32_bf16 v[102:105], v[164:167], v[188:191], v[102:105]
	v_mfma_f32_16x16x32_bf16 v[98:101], v[172:175], v[188:191], v[98:101]
	v_mfma_f32_16x16x32_bf16 v[86:89], v[164:167], v[196:199], v[86:89]
	v_mfma_f32_16x16x32_bf16 v[82:85], v[172:175], v[196:199], v[82:85]
	v_mfma_f32_16x16x32_bf16 v[70:73], v[164:167], v[204:207], v[70:73]
	v_mfma_f32_16x16x32_bf16 v[66:69], v[172:175], v[204:207], v[66:69]
	v_mfma_f32_16x16x32_bf16 v[118:121], v[168:171], v[184:187], v[118:121]
	v_mfma_f32_16x16x32_bf16 v[114:117], v[176:179], v[184:187], v[114:117]
	v_mfma_f32_16x16x32_bf16 v[102:105], v[168:171], v[192:195], v[102:105]
	v_mfma_f32_16x16x32_bf16 v[98:101], v[176:179], v[192:195], v[98:101]
	v_mfma_f32_16x16x32_bf16 v[86:89], v[168:171], v[200:203], v[86:89]
	v_mfma_f32_16x16x32_bf16 v[82:85], v[176:179], v[200:203], v[82:85]
	v_mfma_f32_16x16x32_bf16 v[70:73], v[168:171], v[220:223], v[70:73]
	v_mfma_f32_16x16x32_bf16 v[66:69], v[176:179], v[220:223], v[66:69]
	s_setprio 1
	s_barrier
	s_add_i32 s66, s66, s47
	v_lshl_add_u64 v[208:209], s[64:65], 0, v[132:133]
	s_mov_b32 m0, s66
	ds_read_b128 v[180:183], v147 offset:16384
	ds_read_b128 v[184:187], v147 offset:17408
	ds_read_b128 v[188:191], v147 offset:18432
	ds_read_b128 v[192:195], v147 offset:19456
	ds_read_b128 v[196:199], v147 offset:20480
	ds_read_b128 v[200:203], v147 offset:21504
	ds_read_b128 v[204:207], v147 offset:22528
	ds_read_b128 v[220:223], v147 offset:23552
	global_load_lds_dwordx4 v[208:209], off
	s_add_i32 m0, s66, 0x2000
	v_lshl_add_u64 v[224:225], s[64:65], 0, v[136:137]
	s_add_u32 s64, s64, s45
	s_addc_u32 s65, s65, 0
	s_add_i32 s31, s31, s47
	global_load_lds_dwordx4 v[224:225], off
	v_lshl_add_u64 v[230:231], s[64:65], 0, v[132:133]
	s_mov_b32 m0, s31
	v_lshl_add_u64 v[236:237], s[64:65], 0, v[136:137]
	global_load_lds_dwordx4 v[230:231], off
	s_add_i32 m0, s31, 0x2000
	v_lshl_add_u64 v[238:239], s[38:39], 0, v[130:131]
	global_load_lds_dwordx4 v[236:237], off
	s_mov_b32 m0, s51
	v_lshl_add_u64 v[240:241], s[38:39], 0, v[134:135]
	global_load_lds_dwordx4 v[238:239], off
	s_mov_b32 m0, s52
	s_nop 0
	global_load_lds_dwordx4 v[240:241], off
	s_waitcnt vmcnt(8)
	s_waitcnt lgkmcnt(0)
	s_barrier
	s_setprio 0
	s_waitcnt lgkmcnt(0)
	v_mfma_f32_16x16x32_bf16 v[62:65], v[148:151], v[180:183], v[62:65]
	v_mfma_f32_16x16x32_bf16 v[58:61], v[156:159], v[180:183], v[58:61]
	v_mfma_f32_16x16x32_bf16 v[46:49], v[148:151], v[188:191], v[46:49]
	v_mfma_f32_16x16x32_bf16 v[42:45], v[156:159], v[188:191], v[42:45]
	v_mfma_f32_16x16x32_bf16 v[30:33], v[148:151], v[196:199], v[30:33]
	v_mfma_f32_16x16x32_bf16 v[26:29], v[156:159], v[196:199], v[26:29]
	v_mfma_f32_16x16x32_bf16 v[14:17], v[148:151], v[204:207], v[14:17]
	v_mfma_f32_16x16x32_bf16 v[10:13], v[156:159], v[204:207], v[10:13]
	v_mfma_f32_16x16x32_bf16 v[62:65], v[152:155], v[184:187], v[62:65]
	v_mfma_f32_16x16x32_bf16 v[58:61], v[160:163], v[184:187], v[58:61]
	v_mfma_f32_16x16x32_bf16 v[46:49], v[152:155], v[192:195], v[46:49]
	v_mfma_f32_16x16x32_bf16 v[42:45], v[160:163], v[192:195], v[42:45]
	v_mfma_f32_16x16x32_bf16 v[30:33], v[152:155], v[200:203], v[30:33]
	v_mfma_f32_16x16x32_bf16 v[26:29], v[160:163], v[200:203], v[26:29]
	v_mfma_f32_16x16x32_bf16 v[14:17], v[152:155], v[220:223], v[14:17]
	v_mfma_f32_16x16x32_bf16 v[10:13], v[160:163], v[220:223], v[10:13]
	v_mfma_f32_16x16x32_bf16 v[54:57], v[164:167], v[180:183], v[54:57]
	v_mfma_f32_16x16x32_bf16 v[50:53], v[172:175], v[180:183], v[50:53]
	v_mfma_f32_16x16x32_bf16 v[38:41], v[164:167], v[188:191], v[38:41]
	v_mfma_f32_16x16x32_bf16 v[34:37], v[172:175], v[188:191], v[34:37]
	v_mfma_f32_16x16x32_bf16 v[22:25], v[164:167], v[196:199], v[22:25]
	v_mfma_f32_16x16x32_bf16 v[18:21], v[172:175], v[196:199], v[18:21]
	v_mfma_f32_16x16x32_bf16 v[6:9], v[164:167], v[204:207], v[6:9]
	v_mfma_f32_16x16x32_bf16 v[2:5], v[172:175], v[204:207], v[2:5]
	v_mfma_f32_16x16x32_bf16 v[54:57], v[168:171], v[184:187], v[54:57]
	v_mfma_f32_16x16x32_bf16 v[50:53], v[176:179], v[184:187], v[50:53]
	v_mfma_f32_16x16x32_bf16 v[38:41], v[168:171], v[192:195], v[38:41]
	v_mfma_f32_16x16x32_bf16 v[34:37], v[176:179], v[192:195], v[34:37]
	v_mfma_f32_16x16x32_bf16 v[22:25], v[168:171], v[200:203], v[22:25]
	v_mfma_f32_16x16x32_bf16 v[18:21], v[176:179], v[200:203], v[18:21]
	v_mfma_f32_16x16x32_bf16 v[6:9], v[168:171], v[220:223], v[6:9]
	v_mfma_f32_16x16x32_bf16 v[2:5], v[176:179], v[220:223], v[2:5]
	s_setprio 1
	s_barrier
	s_add_i32 s31, 0, 0x18000
	s_add_i32 s64, 0, 0x1c000
	v_add_u32_e32 v160, s31, v146
	v_add_u32_e32 v176, s64, v146
	ds_read_b128 v[148:151], v160
	ds_read_b128 v[152:155], v160 offset:1024
	ds_read_b128 v[156:159], v160 offset:2048
	ds_read_b128 v[160:163], v160 offset:3072
	ds_read_b128 v[164:167], v176
	ds_read_b128 v[168:171], v176 offset:1024
	ds_read_b128 v[172:175], v176 offset:2048
	ds_read_b128 v[176:179], v176 offset:3072
	s_add_u32 s38, s38, s45
	s_addc_u32 s39, s39, 0
	s_mov_b32 m0, s53
	v_lshl_add_u64 v[242:243], s[38:39], 0, v[130:131]
	ds_read_b128 v[180:183], v147 offset:32768
	ds_read_b128 v[184:187], v147 offset:33792
	ds_read_b128 v[188:191], v147 offset:34816
	ds_read_b128 v[192:195], v147 offset:35840
	ds_read_b128 v[196:199], v147 offset:36864
	ds_read_b128 v[200:203], v147 offset:37888
	ds_read_b128 v[204:207], v147 offset:38912
	ds_read_b128 v[220:223], v147 offset:39936
	global_load_lds_dwordx4 v[242:243], off
	v_lshl_add_u64 v[242:243], s[38:39], 0, v[134:135]
	s_mov_b32 m0, s54
	s_nop 0
	global_load_lds_dwordx4 v[242:243], off
	s_waitcnt vmcnt(8)
	s_waitcnt lgkmcnt(0)
	s_barrier
	s_setprio 0
	s_waitcnt lgkmcnt(0)
	v_mfma_f32_16x16x32_bf16 v[126:129], v[148:151], v[180:183], v[126:129]
	v_mfma_f32_16x16x32_bf16 v[122:125], v[156:159], v[180:183], v[122:125]
	v_mfma_f32_16x16x32_bf16 v[110:113], v[148:151], v[188:191], v[110:113]
	v_mfma_f32_16x16x32_bf16 v[106:109], v[156:159], v[188:191], v[106:109]
	v_mfma_f32_16x16x32_bf16 v[94:97], v[148:151], v[196:199], v[94:97]
	v_mfma_f32_16x16x32_bf16 v[90:93], v[156:159], v[196:199], v[90:93]
	v_mfma_f32_16x16x32_bf16 v[78:81], v[148:151], v[204:207], v[78:81]
	v_mfma_f32_16x16x32_bf16 v[74:77], v[156:159], v[204:207], v[74:77]
	v_mfma_f32_16x16x32_bf16 v[126:129], v[152:155], v[184:187], v[126:129]
	v_mfma_f32_16x16x32_bf16 v[122:125], v[160:163], v[184:187], v[122:125]
	v_mfma_f32_16x16x32_bf16 v[110:113], v[152:155], v[192:195], v[110:113]
	v_mfma_f32_16x16x32_bf16 v[106:109], v[160:163], v[192:195], v[106:109]
	v_mfma_f32_16x16x32_bf16 v[94:97], v[152:155], v[200:203], v[94:97]
	v_mfma_f32_16x16x32_bf16 v[90:93], v[160:163], v[200:203], v[90:93]
	v_mfma_f32_16x16x32_bf16 v[78:81], v[152:155], v[220:223], v[78:81]
	v_mfma_f32_16x16x32_bf16 v[74:77], v[160:163], v[220:223], v[74:77]
	v_mfma_f32_16x16x32_bf16 v[118:121], v[164:167], v[180:183], v[118:121]
	v_mfma_f32_16x16x32_bf16 v[114:117], v[172:175], v[180:183], v[114:117]
	v_mfma_f32_16x16x32_bf16 v[102:105], v[164:167], v[188:191], v[102:105]
	v_mfma_f32_16x16x32_bf16 v[98:101], v[172:175], v[188:191], v[98:101]
	v_mfma_f32_16x16x32_bf16 v[86:89], v[164:167], v[196:199], v[86:89]
	v_mfma_f32_16x16x32_bf16 v[82:85], v[172:175], v[196:199], v[82:85]
	v_mfma_f32_16x16x32_bf16 v[70:73], v[164:167], v[204:207], v[70:73]
	v_mfma_f32_16x16x32_bf16 v[66:69], v[172:175], v[204:207], v[66:69]
	v_mfma_f32_16x16x32_bf16 v[118:121], v[168:171], v[184:187], v[118:121]
	v_mfma_f32_16x16x32_bf16 v[114:117], v[176:179], v[184:187], v[114:117]
	v_mfma_f32_16x16x32_bf16 v[102:105], v[168:171], v[192:195], v[102:105]
	v_mfma_f32_16x16x32_bf16 v[98:101], v[176:179], v[192:195], v[98:101]
	v_mfma_f32_16x16x32_bf16 v[86:89], v[168:171], v[200:203], v[86:89]
	v_mfma_f32_16x16x32_bf16 v[82:85], v[176:179], v[200:203], v[82:85]
	v_mfma_f32_16x16x32_bf16 v[70:73], v[168:171], v[220:223], v[70:73]
	v_mfma_f32_16x16x32_bf16 v[66:69], v[176:179], v[220:223], v[66:69]
	s_setprio 1
	s_barrier
	s_add_i32 s31, s31, s47
	v_lshl_add_u64 v[208:209], v[208:209], 0, s[96:97]
	s_mov_b32 m0, s31
	ds_read_b128 v[180:183], v147 offset:49152
	ds_read_b128 v[184:187], v147 offset:50176
	ds_read_b128 v[188:191], v147 offset:51200
	ds_read_b128 v[192:195], v147 offset:52224
	ds_read_b128 v[196:199], v147 offset:53248
	ds_read_b128 v[200:203], v147 offset:54272
	ds_read_b128 v[204:207], v147 offset:55296
	ds_read_b128 v[220:223], v147 offset:56320
	global_load_lds_dwordx4 v[208:209], off
	v_lshl_add_u64 v[208:209], v[224:225], 0, s[96:97]
	s_add_i32 m0, s31, 0x2000
	s_add_i32 s31, s64, s47
	global_load_lds_dwordx4 v[208:209], off
	v_lshl_add_u64 v[208:209], v[230:231], 0, s[96:97]
	s_mov_b32 m0, s31
	s_nop 0
	global_load_lds_dwordx4 v[208:209], off
	v_lshl_add_u64 v[208:209], v[236:237], 0, s[96:97]
	s_add_i32 m0, s31, 0x2000
	s_nop 0
	global_load_lds_dwordx4 v[208:209], off
	v_lshl_add_u64 v[208:209], v[238:239], 0, s[96:97]
	s_mov_b32 m0, s57
	s_nop 0
	global_load_lds_dwordx4 v[208:209], off
	v_lshl_add_u64 v[208:209], v[240:241], 0, s[96:97]
	s_mov_b32 m0, s58
	s_nop 0
	global_load_lds_dwordx4 v[208:209], off
	s_waitcnt vmcnt(8)
	s_waitcnt lgkmcnt(0)
	s_barrier
	s_setprio 0
	s_waitcnt lgkmcnt(0)
	v_mfma_f32_16x16x32_bf16 v[62:65], v[148:151], v[180:183], v[62:65]
	v_mfma_f32_16x16x32_bf16 v[58:61], v[156:159], v[180:183], v[58:61]
	v_mfma_f32_16x16x32_bf16 v[46:49], v[148:151], v[188:191], v[46:49]
	v_mfma_f32_16x16x32_bf16 v[42:45], v[156:159], v[188:191], v[42:45]
	v_mfma_f32_16x16x32_bf16 v[30:33], v[148:151], v[196:199], v[30:33]
	v_mfma_f32_16x16x32_bf16 v[26:29], v[156:159], v[196:199], v[26:29]
	v_mfma_f32_16x16x32_bf16 v[14:17], v[148:151], v[204:207], v[14:17]
	v_mfma_f32_16x16x32_bf16 v[10:13], v[156:159], v[204:207], v[10:13]
	v_mfma_f32_16x16x32_bf16 v[62:65], v[152:155], v[184:187], v[62:65]
	v_mfma_f32_16x16x32_bf16 v[58:61], v[160:163], v[184:187], v[58:61]
	v_mfma_f32_16x16x32_bf16 v[46:49], v[152:155], v[192:195], v[46:49]
	v_mfma_f32_16x16x32_bf16 v[42:45], v[160:163], v[192:195], v[42:45]
	v_mfma_f32_16x16x32_bf16 v[30:33], v[152:155], v[200:203], v[30:33]
	v_mfma_f32_16x16x32_bf16 v[26:29], v[160:163], v[200:203], v[26:29]
	v_mfma_f32_16x16x32_bf16 v[14:17], v[152:155], v[220:223], v[14:17]
	v_mfma_f32_16x16x32_bf16 v[10:13], v[160:163], v[220:223], v[10:13]
	v_mfma_f32_16x16x32_bf16 v[54:57], v[164:167], v[180:183], v[54:57]
	v_mfma_f32_16x16x32_bf16 v[50:53], v[172:175], v[180:183], v[50:53]
	v_mfma_f32_16x16x32_bf16 v[38:41], v[164:167], v[188:191], v[38:41]
	v_mfma_f32_16x16x32_bf16 v[34:37], v[172:175], v[188:191], v[34:37]
	v_mfma_f32_16x16x32_bf16 v[22:25], v[164:167], v[196:199], v[22:25]
	v_mfma_f32_16x16x32_bf16 v[18:21], v[172:175], v[196:199], v[18:21]
	v_mfma_f32_16x16x32_bf16 v[6:9], v[164:167], v[204:207], v[6:9]
	v_mfma_f32_16x16x32_bf16 v[2:5], v[172:175], v[204:207], v[2:5]
	v_mfma_f32_16x16x32_bf16 v[54:57], v[168:171], v[184:187], v[54:57]
	v_mfma_f32_16x16x32_bf16 v[50:53], v[176:179], v[184:187], v[50:53]
	v_mfma_f32_16x16x32_bf16 v[38:41], v[168:171], v[192:195], v[38:41]
	v_mfma_f32_16x16x32_bf16 v[34:37], v[176:179], v[192:195], v[34:37]
	v_mfma_f32_16x16x32_bf16 v[22:25], v[168:171], v[200:203], v[22:25]
	v_mfma_f32_16x16x32_bf16 v[18:21], v[176:179], v[200:203], v[18:21]
	v_mfma_f32_16x16x32_bf16 v[6:9], v[168:171], v[220:223], v[6:9]
	v_mfma_f32_16x16x32_bf16 v[2:5], v[176:179], v[220:223], v[2:5]
	s_setprio 1
	s_barrier
	s_add_u32 s36, s36, 0x100
	s_addc_u32 s37, s37, 0
	v_lshl_add_u64 v[144:145], v[144:145], 0, s[2:3]
	v_lshl_add_u64 v[142:143], v[142:143], 0, s[2:3]
	s_cmp_ge_u32 s63, s56
	s_mov_b32 s31, s63
	s_cbranch_scc0 .LBB0_476
	s_and_b64 vcc, exec, s[6:7]
	s_cbranch_vccnz .LBB0_464
	v_mov_b32_e32 v2, 0
	s_mov_b32 s55, s61
	s_mov_b32 s50, s62
	s_mov_b64 s[26:27], s[34:35]
	s_mov_b64 s[28:29], s[8:9]
	s_mov_b32 s60, s30
	v_mov_b32_e32 v3, v2
	v_mov_b32_e32 v4, v2
	v_mov_b32_e32 v5, v2
	v_mov_b32_e32 v6, v2
	v_mov_b32_e32 v7, v2
	v_mov_b32_e32 v8, v2
	v_mov_b32_e32 v9, v2
	v_mov_b32_e32 v18, v2
	v_mov_b32_e32 v19, v2
	v_mov_b32_e32 v20, v2
	v_mov_b32_e32 v21, v2
	v_mov_b32_e32 v22, v2
	v_mov_b32_e32 v23, v2
	v_mov_b32_e32 v24, v2
	v_mov_b32_e32 v25, v2
	v_mov_b32_e32 v34, v2
	v_mov_b32_e32 v35, v2
	v_mov_b32_e32 v36, v2
	v_mov_b32_e32 v37, v2
	v_mov_b32_e32 v38, v2
	v_mov_b32_e32 v39, v2
	v_mov_b32_e32 v40, v2
	v_mov_b32_e32 v41, v2
	v_mov_b32_e32 v50, v2
	v_mov_b32_e32 v51, v2
	v_mov_b32_e32 v52, v2
	v_mov_b32_e32 v53, v2
	v_mov_b32_e32 v54, v2
	v_mov_b32_e32 v55, v2
	v_mov_b32_e32 v56, v2
	v_mov_b32_e32 v57, v2
	v_mov_b32_e32 v10, v2
	v_mov_b32_e32 v11, v2
	v_mov_b32_e32 v12, v2
	v_mov_b32_e32 v13, v2
	v_mov_b32_e32 v14, v2
	v_mov_b32_e32 v15, v2
	v_mov_b32_e32 v16, v2
	v_mov_b32_e32 v17, v2
	v_mov_b32_e32 v26, v2
	v_mov_b32_e32 v27, v2
	v_mov_b32_e32 v28, v2
	v_mov_b32_e32 v29, v2
	v_mov_b32_e32 v30, v2
	v_mov_b32_e32 v31, v2
	v_mov_b32_e32 v32, v2
	v_mov_b32_e32 v33, v2
	v_mov_b32_e32 v42, v2
	v_mov_b32_e32 v43, v2
	v_mov_b32_e32 v44, v2
	v_mov_b32_e32 v45, v2
	v_mov_b32_e32 v46, v2
	v_mov_b32_e32 v47, v2
	v_mov_b32_e32 v48, v2
	v_mov_b32_e32 v49, v2
	v_mov_b32_e32 v58, v2
	v_mov_b32_e32 v59, v2
	v_mov_b32_e32 v60, v2
	v_mov_b32_e32 v61, v2
	v_mov_b32_e32 v62, v2
	v_mov_b32_e32 v63, v2
	v_mov_b32_e32 v64, v2
	v_mov_b32_e32 v65, v2
	v_mov_b32_e32 v66, v2
	v_mov_b32_e32 v67, v2
	v_mov_b32_e32 v68, v2
	v_mov_b32_e32 v69, v2
	v_mov_b32_e32 v70, v2
	v_mov_b32_e32 v71, v2
	v_mov_b32_e32 v72, v2
	v_mov_b32_e32 v73, v2
	v_mov_b32_e32 v82, v2
	v_mov_b32_e32 v83, v2
	v_mov_b32_e32 v84, v2
	v_mov_b32_e32 v85, v2
	v_mov_b32_e32 v86, v2
	v_mov_b32_e32 v87, v2
	v_mov_b32_e32 v88, v2
	v_mov_b32_e32 v89, v2
	v_mov_b32_e32 v98, v2
	v_mov_b32_e32 v99, v2
	v_mov_b32_e32 v100, v2
	v_mov_b32_e32 v101, v2
	v_mov_b32_e32 v102, v2
	v_mov_b32_e32 v103, v2
	v_mov_b32_e32 v104, v2
	v_mov_b32_e32 v105, v2
	v_mov_b32_e32 v114, v2
	v_mov_b32_e32 v115, v2
	v_mov_b32_e32 v116, v2
	v_mov_b32_e32 v117, v2
	v_mov_b32_e32 v118, v2
	v_mov_b32_e32 v119, v2
	v_mov_b32_e32 v120, v2
	v_mov_b32_e32 v121, v2
	v_mov_b32_e32 v74, v2
	v_mov_b32_e32 v75, v2
	v_mov_b32_e32 v76, v2
	v_mov_b32_e32 v77, v2
	v_mov_b32_e32 v78, v2
	v_mov_b32_e32 v79, v2
	v_mov_b32_e32 v80, v2
	v_mov_b32_e32 v81, v2
	v_mov_b32_e32 v90, v2
	v_mov_b32_e32 v91, v2
	v_mov_b32_e32 v92, v2
	v_mov_b32_e32 v93, v2
	v_mov_b32_e32 v94, v2
	v_mov_b32_e32 v95, v2
	v_mov_b32_e32 v96, v2
	v_mov_b32_e32 v97, v2
	v_mov_b32_e32 v106, v2
	v_mov_b32_e32 v107, v2
	v_mov_b32_e32 v108, v2
	v_mov_b32_e32 v109, v2
	v_mov_b32_e32 v110, v2
	v_mov_b32_e32 v111, v2
	v_mov_b32_e32 v112, v2
	v_mov_b32_e32 v113, v2
	v_mov_b32_e32 v122, v2
	v_mov_b32_e32 v123, v2
	v_mov_b32_e32 v124, v2
	v_mov_b32_e32 v125, v2
	v_mov_b32_e32 v126, v2
	v_mov_b32_e32 v127, v2
	v_mov_b32_e32 v128, v2
	v_mov_b32_e32 v129, v2
	s_branch .LBB0_464

.LBB0_640:
	s_add_u32 s22, s20, 0xfffc0080
	s_addc_u32 s23, s21, -1
	s_add_i32 s46, 0, 0x10000
	s_cmp_eq_u32 s45, 12
	s_cselect_b32 s25, s13, s23
	s_cselect_b32 s24, s19, s22
	v_add_u32_e32 v150, s46, v159
	s_cselect_b32 s23, s11, s44
	s_cselect_b32 s22, s41, s43
	s_add_i32 s48, 0, 0x14000
	ds_read_b128 v[164:167], v150
	ds_read_b128 v[168:171], v150 offset:1024
	ds_read_b128 v[172:175], v150 offset:2048
	ds_read_b128 v[176:179], v150 offset:3072
	v_add_u32_e32 v150, s48, v159
	ds_read_b128 v[180:183], v150
	ds_read_b128 v[184:187], v150 offset:1024
	ds_read_b128 v[188:191], v150 offset:2048
	ds_read_b128 v[192:195], v150 offset:3072
	v_lshl_add_u64 v[150:151], s[20:21], 0, v[140:141]
	s_add_i32 m0, s30, 0xc000
	ds_read_b128 v[196:199], v162
	ds_read_b128 v[200:203], v162 offset:1024
	ds_read_b128 v[204:207], v162 offset:2048
	ds_read_b128 v[220:223], v162 offset:3072
	ds_read_b128 v[236:239], v162 offset:4096
	ds_read_b128 v[240:243], v162 offset:5120
	ds_read_b128 v[244:247], v162 offset:6144
	ds_read_b128 v[248:251], v162 offset:7168
	global_load_lds_dwordx4 v[150:151], off
	v_lshl_add_u64 v[150:151], s[20:21], 0, v[138:139]
	s_add_i32 m0, s30, 0xe000
	s_nop 0
	global_load_lds_dwordx4 v[150:151], off
	s_waitcnt vmcnt(8)
	s_waitcnt lgkmcnt(0)
	s_barrier
	s_setprio 0
	s_waitcnt lgkmcnt(0)
	v_mfma_f32_16x16x32_bf16 v[126:129], v[164:167], v[196:199], v[126:129]
	v_mfma_f32_16x16x32_bf16 v[122:125], v[172:175], v[196:199], v[122:125]
	v_mfma_f32_16x16x32_bf16 v[118:121], v[164:167], v[204:207], v[118:121]
	v_mfma_f32_16x16x32_bf16 v[114:117], v[172:175], v[204:207], v[114:117]
	v_mfma_f32_16x16x32_bf16 v[110:113], v[164:167], v[236:239], v[110:113]
	v_mfma_f32_16x16x32_bf16 v[106:109], v[172:175], v[236:239], v[106:109]
	v_mfma_f32_16x16x32_bf16 v[102:105], v[164:167], v[244:247], v[102:105]
	v_mfma_f32_16x16x32_bf16 v[98:101], v[172:175], v[244:247], v[98:101]
	v_mfma_f32_16x16x32_bf16 v[126:129], v[168:171], v[200:203], v[126:129]
	v_mfma_f32_16x16x32_bf16 v[122:125], v[176:179], v[200:203], v[122:125]
	v_mfma_f32_16x16x32_bf16 v[118:121], v[168:171], v[220:223], v[118:121]
	v_mfma_f32_16x16x32_bf16 v[114:117], v[176:179], v[220:223], v[114:117]
	v_mfma_f32_16x16x32_bf16 v[110:113], v[168:171], v[240:243], v[110:113]
	v_mfma_f32_16x16x32_bf16 v[106:109], v[176:179], v[240:243], v[106:109]
	v_mfma_f32_16x16x32_bf16 v[102:105], v[168:171], v[248:251], v[102:105]
	v_mfma_f32_16x16x32_bf16 v[98:101], v[176:179], v[248:251], v[98:101]
	v_mfma_f32_16x16x32_bf16 v[94:97], v[180:183], v[196:199], v[94:97]
	v_mfma_f32_16x16x32_bf16 v[90:93], v[188:191], v[196:199], v[90:93]
	v_mfma_f32_16x16x32_bf16 v[86:89], v[180:183], v[204:207], v[86:89]
	v_mfma_f32_16x16x32_bf16 v[82:85], v[188:191], v[204:207], v[82:85]
	v_mfma_f32_16x16x32_bf16 v[78:81], v[180:183], v[236:239], v[78:81]
	v_mfma_f32_16x16x32_bf16 v[74:77], v[188:191], v[236:239], v[74:77]
	v_mfma_f32_16x16x32_bf16 v[70:73], v[180:183], v[244:247], v[70:73]
	v_mfma_f32_16x16x32_bf16 v[66:69], v[188:191], v[244:247], v[66:69]
	v_mfma_f32_16x16x32_bf16 v[94:97], v[184:187], v[200:203], v[94:97]
	v_mfma_f32_16x16x32_bf16 v[90:93], v[192:195], v[200:203], v[90:93]
	v_mfma_f32_16x16x32_bf16 v[86:89], v[184:187], v[220:223], v[86:89]
	v_mfma_f32_16x16x32_bf16 v[82:85], v[192:195], v[220:223], v[82:85]
	v_mfma_f32_16x16x32_bf16 v[78:81], v[184:187], v[240:243], v[78:81]
	v_mfma_f32_16x16x32_bf16 v[74:77], v[192:195], v[240:243], v[74:77]
	v_mfma_f32_16x16x32_bf16 v[70:73], v[184:187], v[248:251], v[70:73]
	v_mfma_f32_16x16x32_bf16 v[66:69], v[192:195], v[248:251], v[66:69]
	s_setprio 1
	s_barrier
	s_add_i32 s46, s46, s28
	v_lshl_add_u64 v[150:151], s[22:23], 0, v[134:135]
	s_mov_b32 m0, s46
	ds_read_b128 v[196:199], v162 offset:16384
	ds_read_b128 v[200:203], v162 offset:17408
	ds_read_b128 v[204:207], v162 offset:18432
	ds_read_b128 v[220:223], v162 offset:19456
	ds_read_b128 v[236:239], v162 offset:20480
	ds_read_b128 v[240:243], v162 offset:21504
	ds_read_b128 v[244:247], v162 offset:22528
	ds_read_b128 v[248:251], v162 offset:23552
	global_load_lds_dwordx4 v[150:151], off
	s_add_i32 m0, s46, 0x2000
	s_add_u32 s46, s22, 0x40000
	v_lshl_add_u64 v[208:209], s[22:23], 0, v[130:131]
	s_addc_u32 s47, s23, 0
	s_add_i32 s48, s48, s28
	global_load_lds_dwordx4 v[208:209], off
	v_lshl_add_u64 v[224:225], s[46:47], 0, v[134:135]
	s_mov_b32 m0, s48
	v_lshl_add_u64 v[252:253], s[24:25], 0, v[132:133]
	global_load_lds_dwordx4 v[224:225], off
	v_lshl_add_u64 v[224:225], s[46:47], 0, v[130:131]
	s_add_i32 m0, s48, 0x2000
	s_nop 0
	global_load_lds_dwordx4 v[224:225], off
	v_lshl_add_u64 v[224:225], s[24:25], 0, v[136:137]
	s_mov_b32 m0, s30
	s_nop 0
	global_load_lds_dwordx4 v[224:225], off
	s_mov_b32 m0, s31
	s_nop 0
	global_load_lds_dwordx4 v[252:253], off
	s_waitcnt vmcnt(8)
	s_waitcnt lgkmcnt(0)
	s_barrier
	s_setprio 0
	s_waitcnt lgkmcnt(0)
	v_mfma_f32_16x16x32_bf16 v[62:65], v[164:167], v[196:199], v[62:65]
	v_mfma_f32_16x16x32_bf16 v[58:61], v[172:175], v[196:199], v[58:61]
	v_mfma_f32_16x16x32_bf16 v[54:57], v[164:167], v[204:207], v[54:57]
	v_mfma_f32_16x16x32_bf16 v[50:53], v[172:175], v[204:207], v[50:53]
	v_mfma_f32_16x16x32_bf16 v[46:49], v[164:167], v[236:239], v[46:49]
	v_mfma_f32_16x16x32_bf16 v[42:45], v[172:175], v[236:239], v[42:45]
	v_mfma_f32_16x16x32_bf16 v[38:41], v[164:167], v[244:247], v[38:41]
	v_mfma_f32_16x16x32_bf16 v[34:37], v[172:175], v[244:247], v[34:37]
	v_mfma_f32_16x16x32_bf16 v[62:65], v[168:171], v[200:203], v[62:65]
	v_mfma_f32_16x16x32_bf16 v[58:61], v[176:179], v[200:203], v[58:61]
	v_mfma_f32_16x16x32_bf16 v[54:57], v[168:171], v[220:223], v[54:57]
	v_mfma_f32_16x16x32_bf16 v[50:53], v[176:179], v[220:223], v[50:53]
	v_mfma_f32_16x16x32_bf16 v[46:49], v[168:171], v[240:243], v[46:49]
	v_mfma_f32_16x16x32_bf16 v[42:45], v[176:179], v[240:243], v[42:45]
	v_mfma_f32_16x16x32_bf16 v[38:41], v[168:171], v[248:251], v[38:41]
	v_mfma_f32_16x16x32_bf16 v[34:37], v[176:179], v[248:251], v[34:37]
	v_mfma_f32_16x16x32_bf16 v[30:33], v[180:183], v[196:199], v[30:33]
	v_mfma_f32_16x16x32_bf16 v[26:29], v[188:191], v[196:199], v[26:29]
	v_mfma_f32_16x16x32_bf16 v[22:25], v[180:183], v[204:207], v[22:25]
	v_mfma_f32_16x16x32_bf16 v[18:21], v[188:191], v[204:207], v[18:21]
	v_mfma_f32_16x16x32_bf16 v[14:17], v[180:183], v[236:239], v[14:17]
	v_mfma_f32_16x16x32_bf16 v[10:13], v[188:191], v[236:239], v[10:13]
	v_mfma_f32_16x16x32_bf16 v[6:9], v[180:183], v[244:247], v[6:9]
	v_mfma_f32_16x16x32_bf16 v[2:5], v[188:191], v[244:247], v[2:5]
	v_mfma_f32_16x16x32_bf16 v[30:33], v[184:187], v[200:203], v[30:33]
	v_mfma_f32_16x16x32_bf16 v[26:29], v[192:195], v[200:203], v[26:29]
	v_mfma_f32_16x16x32_bf16 v[22:25], v[184:187], v[220:223], v[22:25]
	v_mfma_f32_16x16x32_bf16 v[18:21], v[192:195], v[220:223], v[18:21]
	v_mfma_f32_16x16x32_bf16 v[14:17], v[184:187], v[240:243], v[14:17]
	v_mfma_f32_16x16x32_bf16 v[10:13], v[192:195], v[240:243], v[10:13]
	v_mfma_f32_16x16x32_bf16 v[6:9], v[184:187], v[248:251], v[6:9]
	v_mfma_f32_16x16x32_bf16 v[2:5], v[192:195], v[248:251], v[2:5]
	s_setprio 1
	s_barrier
	s_add_i32 s46, 0, 0x18000
	v_add_u32_e32 v163, s46, v159
	s_add_i32 s47, 0, 0x1c000
	ds_read_b128 v[164:167], v163
	ds_read_b128 v[168:171], v163 offset:1024
	ds_read_b128 v[172:175], v163 offset:2048
	ds_read_b128 v[176:179], v163 offset:3072
	v_add_u32_e32 v163, s47, v159
	ds_read_b128 v[180:183], v163
	ds_read_b128 v[184:187], v163 offset:1024
	ds_read_b128 v[188:191], v163 offset:2048
	ds_read_b128 v[192:195], v163 offset:3072
	s_add_u32 s24, s24, 0x40000
	s_addc_u32 s25, s25, 0
	s_mov_b32 m0, s34
	v_lshl_add_u64 v[230:231], s[24:25], 0, v[136:137]
	ds_read_b128 v[196:199], v162 offset:32768
	ds_read_b128 v[200:203], v162 offset:33792
	ds_read_b128 v[204:207], v162 offset:34816
	ds_read_b128 v[220:223], v162 offset:35840
	ds_read_b128 v[236:239], v162 offset:36864
	ds_read_b128 v[240:243], v162 offset:37888
	ds_read_b128 v[244:247], v162 offset:38912
	ds_read_b128 v[248:251], v162 offset:39936
	global_load_lds_dwordx4 v[230:231], off
	v_lshl_add_u64 v[230:231], s[24:25], 0, v[132:133]
	s_mov_b32 m0, s35
	s_nop 0
	global_load_lds_dwordx4 v[230:231], off
	s_waitcnt vmcnt(8)
	s_waitcnt lgkmcnt(0)
	s_barrier
	s_setprio 0
	s_waitcnt lgkmcnt(0)
	v_mfma_f32_16x16x32_bf16 v[126:129], v[164:167], v[196:199], v[126:129]
	v_mfma_f32_16x16x32_bf16 v[122:125], v[172:175], v[196:199], v[122:125]
	v_mfma_f32_16x16x32_bf16 v[118:121], v[164:167], v[204:207], v[118:121]
	v_mfma_f32_16x16x32_bf16 v[114:117], v[172:175], v[204:207], v[114:117]
	v_mfma_f32_16x16x32_bf16 v[110:113], v[164:167], v[236:239], v[110:113]
	v_mfma_f32_16x16x32_bf16 v[106:109], v[172:175], v[236:239], v[106:109]
	v_mfma_f32_16x16x32_bf16 v[102:105], v[164:167], v[244:247], v[102:105]
	v_mfma_f32_16x16x32_bf16 v[98:101], v[172:175], v[244:247], v[98:101]
	v_mfma_f32_16x16x32_bf16 v[126:129], v[168:171], v[200:203], v[126:129]
	v_mfma_f32_16x16x32_bf16 v[122:125], v[176:179], v[200:203], v[122:125]
	v_mfma_f32_16x16x32_bf16 v[118:121], v[168:171], v[220:223], v[118:121]
	v_mfma_f32_16x16x32_bf16 v[114:117], v[176:179], v[220:223], v[114:117]
	v_mfma_f32_16x16x32_bf16 v[110:113], v[168:171], v[240:243], v[110:113]
	v_mfma_f32_16x16x32_bf16 v[106:109], v[176:179], v[240:243], v[106:109]
	v_mfma_f32_16x16x32_bf16 v[102:105], v[168:171], v[248:251], v[102:105]
	v_mfma_f32_16x16x32_bf16 v[98:101], v[176:179], v[248:251], v[98:101]
	v_mfma_f32_16x16x32_bf16 v[94:97], v[180:183], v[196:199], v[94:97]
	v_mfma_f32_16x16x32_bf16 v[90:93], v[188:191], v[196:199], v[90:93]
	v_mfma_f32_16x16x32_bf16 v[86:89], v[180:183], v[204:207], v[86:89]
	v_mfma_f32_16x16x32_bf16 v[82:85], v[188:191], v[204:207], v[82:85]
	v_mfma_f32_16x16x32_bf16 v[78:81], v[180:183], v[236:239], v[78:81]
	v_mfma_f32_16x16x32_bf16 v[74:77], v[188:191], v[236:239], v[74:77]
	v_mfma_f32_16x16x32_bf16 v[70:73], v[180:183], v[244:247], v[70:73]
	v_mfma_f32_16x16x32_bf16 v[66:69], v[188:191], v[244:247], v[66:69]
	v_mfma_f32_16x16x32_bf16 v[94:97], v[184:187], v[200:203], v[94:97]
	v_mfma_f32_16x16x32_bf16 v[90:93], v[192:195], v[200:203], v[90:93]
	v_mfma_f32_16x16x32_bf16 v[86:89], v[184:187], v[220:223], v[86:89]
	v_mfma_f32_16x16x32_bf16 v[82:85], v[192:195], v[220:223], v[82:85]
	v_mfma_f32_16x16x32_bf16 v[78:81], v[184:187], v[240:243], v[78:81]
	v_mfma_f32_16x16x32_bf16 v[74:77], v[192:195], v[240:243], v[74:77]
	v_mfma_f32_16x16x32_bf16 v[70:73], v[184:187], v[248:251], v[70:73]
	v_mfma_f32_16x16x32_bf16 v[66:69], v[192:195], v[248:251], v[66:69]
	s_setprio 1
	s_barrier
	s_add_i32 s24, s46, s28
	v_lshl_add_u64 v[150:151], v[150:151], 0, s[96:97]
	s_mov_b32 m0, s24
	ds_read_b128 v[196:199], v162 offset:49152
	ds_read_b128 v[200:203], v162 offset:50176
	ds_read_b128 v[204:207], v162 offset:51200
	ds_read_b128 v[220:223], v162 offset:52224
	ds_read_b128 v[236:239], v162 offset:53248
	ds_read_b128 v[240:243], v162 offset:54272
	ds_read_b128 v[244:247], v162 offset:55296
	ds_read_b128 v[248:251], v162 offset:56320
	global_load_lds_dwordx4 v[150:151], off
	s_add_i32 m0, s24, 0x2000
	s_add_u32 s22, s22, 0x40080
	v_lshl_add_u64 v[150:151], v[208:209], 0, s[96:97]
	s_addc_u32 s23, s23, 0
	s_add_i32 s24, s47, s28
	global_load_lds_dwordx4 v[150:151], off
	v_lshl_add_u64 v[150:151], s[22:23], 0, v[134:135]
	s_mov_b32 m0, s24
	s_nop 0
	global_load_lds_dwordx4 v[150:151], off
	v_lshl_add_u64 v[150:151], s[22:23], 0, v[130:131]
	s_add_i32 m0, s24, 0x2000
	s_nop 0
	global_load_lds_dwordx4 v[150:151], off
	v_lshl_add_u64 v[150:151], v[224:225], 0, s[96:97]
	s_mov_b32 m0, s36
	s_nop 0
	global_load_lds_dwordx4 v[150:151], off
	v_lshl_add_u64 v[150:151], v[252:253], 0, s[96:97]
	s_mov_b32 m0, s37
	s_nop 0
	global_load_lds_dwordx4 v[150:151], off
	s_waitcnt vmcnt(8)
	s_waitcnt lgkmcnt(0)
	s_barrier
	s_setprio 0
	s_waitcnt lgkmcnt(0)
	v_mfma_f32_16x16x32_bf16 v[62:65], v[164:167], v[196:199], v[62:65]
	v_mfma_f32_16x16x32_bf16 v[58:61], v[172:175], v[196:199], v[58:61]
	v_mfma_f32_16x16x32_bf16 v[54:57], v[164:167], v[204:207], v[54:57]
	v_mfma_f32_16x16x32_bf16 v[50:53], v[172:175], v[204:207], v[50:53]
	v_mfma_f32_16x16x32_bf16 v[46:49], v[164:167], v[236:239], v[46:49]
	v_mfma_f32_16x16x32_bf16 v[42:45], v[172:175], v[236:239], v[42:45]
	v_mfma_f32_16x16x32_bf16 v[38:41], v[164:167], v[244:247], v[38:41]
	v_mfma_f32_16x16x32_bf16 v[34:37], v[172:175], v[244:247], v[34:37]
	v_mfma_f32_16x16x32_bf16 v[62:65], v[168:171], v[200:203], v[62:65]
	v_mfma_f32_16x16x32_bf16 v[58:61], v[176:179], v[200:203], v[58:61]
	v_mfma_f32_16x16x32_bf16 v[54:57], v[168:171], v[220:223], v[54:57]
	v_mfma_f32_16x16x32_bf16 v[50:53], v[176:179], v[220:223], v[50:53]
	v_mfma_f32_16x16x32_bf16 v[46:49], v[168:171], v[240:243], v[46:49]
	v_mfma_f32_16x16x32_bf16 v[42:45], v[176:179], v[240:243], v[42:45]
	v_mfma_f32_16x16x32_bf16 v[38:41], v[168:171], v[248:251], v[38:41]
	v_mfma_f32_16x16x32_bf16 v[34:37], v[176:179], v[248:251], v[34:37]
	v_mfma_f32_16x16x32_bf16 v[30:33], v[180:183], v[196:199], v[30:33]
	v_mfma_f32_16x16x32_bf16 v[26:29], v[188:191], v[196:199], v[26:29]
	v_mfma_f32_16x16x32_bf16 v[22:25], v[180:183], v[204:207], v[22:25]
	v_mfma_f32_16x16x32_bf16 v[18:21], v[188:191], v[204:207], v[18:21]
	v_mfma_f32_16x16x32_bf16 v[14:17], v[180:183], v[236:239], v[14:17]
	v_mfma_f32_16x16x32_bf16 v[10:13], v[188:191], v[236:239], v[10:13]
	v_mfma_f32_16x16x32_bf16 v[6:9], v[180:183], v[244:247], v[6:9]
	v_mfma_f32_16x16x32_bf16 v[2:5], v[188:191], v[244:247], v[2:5]
	v_mfma_f32_16x16x32_bf16 v[30:33], v[184:187], v[200:203], v[30:33]
	v_mfma_f32_16x16x32_bf16 v[26:29], v[192:195], v[200:203], v[26:29]
	v_mfma_f32_16x16x32_bf16 v[22:25], v[184:187], v[220:223], v[22:25]
	v_mfma_f32_16x16x32_bf16 v[18:21], v[192:195], v[220:223], v[18:21]
	v_mfma_f32_16x16x32_bf16 v[14:17], v[184:187], v[240:243], v[14:17]
	v_mfma_f32_16x16x32_bf16 v[10:13], v[192:195], v[240:243], v[10:13]
	v_mfma_f32_16x16x32_bf16 v[6:9], v[184:187], v[248:251], v[6:9]
	v_mfma_f32_16x16x32_bf16 v[2:5], v[192:195], v[248:251], v[2:5]
	s_setprio 1
	s_barrier
	s_add_i32 s45, s45, 2
	s_add_u32 s43, s43, 0x100
	s_addc_u32 s44, s44, 0
	s_add_u32 s20, s20, 0x100
	s_addc_u32 s21, s21, 0
	s_cmp_gt_u32 s45, 13
	s_cbranch_scc0 .LBB0_640
	s_and_b64 vcc, exec, s[8:9]
	s_cbranch_vccz .LBB0_643
	s_barrier
